# GEMM phase prologues: both k-steps' stage loads issued back to back (mid-prologue vmcnt(2)+barrier removed, late wave half's stagger barrier moved behind the loads)
# baseline (speedup 1.0000x reference)
.LBB0_125:
	s_add_u32 s14, s6, 0x6200000
	s_addc_u32 s15, s7, 0
	s_ashr_i32 s55, s54, 31
	s_lshl_b64 s[16:17], s[54:55], 16
	s_add_u32 s6, s6, s16
	s_addc_u32 s7, s7, s17
	s_add_u32 s16, s6, 0xf110000
	s_addc_u32 s17, s7, 0
	s_and_b32 s20, s20, 3
	s_add_i32 m0, s41, 0x18000
	v_lshl_add_u64 v[8:9], v[8:9], 0, s[90:91]
	s_lshl_b32 s21, s19, 13
	s_lshl_b32 s22, s20, 12
	global_load_lds_dwordx4 v[8:9], off
	v_lshl_add_u64 v[6:7], v[6:7], 0, s[90:91]
	s_add_i32 m0, s41, 0x1a000
	s_add_i32 s45, s41, 0x8000
	s_add_i32 s51, s41, 0xa000
	global_load_lds_dwordx4 v[6:7], off
	v_lshl_add_u64 v[2:3], v[2:3], 0, s[90:91]
	s_mov_b32 m0, s45
	s_add_u32 s6, s10, 0x40080
	global_load_lds_dwordx4 v[2:3], off
	v_lshl_add_u64 v[2:3], v[4:5], 0, s[90:91]
	s_mov_b32 m0, s51
	s_addc_u32 s7, s11, 0
	global_load_lds_dwordx4 v[2:3], off
	s_add_i32 m0, s41, 0x1c000
	v_lshl_add_u64 v[2:3], s[6:7], 0, v[134:135]
	global_load_lds_dwordx4 v[2:3], off
	v_lshl_add_u64 v[2:3], s[6:7], 0, v[130:131]
	s_add_i32 m0, s41, 0x1e000
	s_cmpk_lt_u32 s18, 0x100
	global_load_lds_dwordx4 v[2:3], off
	v_bfe_u32 v3, v11, 4, 2
	v_and_b32_e32 v2, 15, v11
	v_lshlrev_b32_e32 v5, 4, v3
	v_lshl_or_b32 v147, s19, 6, v2
	v_lshlrev_b32_e32 v4, 3, v3
	v_lshl_or_b32 v2, v2, 6, v5
	v_lshlrev_b32_e32 v5, 2, v11
	v_lshlrev_b32_e32 v3, 2, v3
	v_and_b32_e32 v5, 32, v5
	v_lshl_or_b32 v3, s20, 4, v3
	v_bitop3_b32 v6, v2, s21, v5 bitop3:0xde
	v_bitop3_b32 v166, v2, s22, v5 bitop3:0xde
	v_lshl_or_b32 v2, s20, 5, v4
	v_cvt_f32_ubyte0_e32 v4, v3
	v_or_b32_e32 v5, 1, v3
	v_or_b32_e32 v7, 2, v3
	v_or_b32_e32 v3, 3, v3
	v_cvt_f32_ubyte0_e32 v3, v3
	v_mul_f32_e32 v3, 0xbe57fa62, v3
	v_exp_f32_e32 v3, v3
	v_mul_f32_e32 v4, 0xbe57fa62, v4
	v_exp_f32_e32 v4, v4
	v_cvt_f32_ubyte0_e32 v5, v5
	v_mul_f32_e32 v170, 0.15915494, v3
	v_lshlrev_b32_e32 v3, 14, v14
	v_and_b32_e32 v3, 0xffff8000, v3
	v_cvt_f32_ubyte0_e32 v7, v7
	v_mul_f32_e32 v167, 0.15915494, v4
	v_lshl_add_u32 v3, v13, 11, v3
	v_and_b32_e32 v4, 1, v14
	v_mul_f32_e32 v5, 0xbe57fa62, v5
	v_mul_f32_e32 v7, 0xbe57fa62, v7
	v_lshl_or_b32 v3, v4, 6, v3
	v_exp_f32_e32 v5, v5
	v_exp_f32_e32 v7, v7
	v_lshl_add_u32 v138, v15, 1, v3
	v_lshlrev_b32_e32 v3, 14, v0
	v_and_b32_e32 v3, 0xffff8000, v3
	s_waitcnt vmcnt(6)
	v_lshl_add_u32 v3, v10, 11, v3
	v_and_b32_e32 v0, 1, v0
	v_lshl_or_b32 v0, v0, 6, v3
	v_readlane_b32 s4, v255, 27
	s_cselect_b64 s[18:19], -1, 0
	v_mul_f32_e32 v168, 0.15915494, v5
	v_mul_f32_e32 v169, 0.15915494, v7
	v_mov_b32_e32 v139, v1
	v_lshl_add_u32 v140, v12, 1, v0
	v_mov_b32_e32 v141, v1
	s_mov_b32 s55, 0
	v_add_u32_e32 v171, 0, v6
	v_lshlrev_b32_e32 v0, 1, v2
	v_readlane_b32 s56, v255, 13
	s_mov_b32 s57, s4
	s_movk_i32 s4, 0x71
	s_andn2_b64 vcc, exec, s[12:13]
	s_cbranch_vccnz .Lpd_g1
	s_barrier
.Lpd_g1:
	s_barrier
	v_readlane_b32 s5, v255, 28
	s_branch .LBB0_128

.LBB0_335:
	s_add_u32 s10, s6, 0xe200000
	s_addc_u32 s11, s7, 0
	s_add_u32 s12, s6, 0xf180000
	s_addc_u32 s13, s7, 0
	v_bfe_u32 v17, v15, 4, 2
	s_add_u32 s14, s6, 0xf000000
	v_and_b32_e32 v16, 15, v15
	v_lshlrev_b32_e32 v19, 4, v17
	v_lshlrev_b32_e32 v15, 2, v15
	s_addc_u32 s15, s7, 0
	s_and_b32 s57, s18, 3
	v_lshl_or_b32 v139, s17, 6, v16
	v_lshl_or_b32 v16, v16, 6, v19
	s_lshl_b32 s6, s17, 13
	v_and_b32_e32 v15, 32, v15
	s_add_i32 m0, s45, 0x18000
	v_lshl_add_u64 v[8:9], v[8:9], 0, s[90:91]
	v_bitop3_b32 v19, v16, s6, v15 bitop3:0xde
	s_lshl_b32 s6, s57, 12
	global_load_lds_dwordx4 v[8:9], off
	v_lshl_add_u64 v[6:7], v[6:7], 0, s[90:91]
	s_add_i32 m0, s45, 0x1a000
	s_add_i32 s58, s45, 0x8000
	s_add_i32 s59, s45, 0xa000
	v_bitop3_b32 v152, v16, s6, v15 bitop3:0xde
	global_load_lds_dwordx4 v[6:7], off
	v_lshl_add_u64 v[2:3], v[2:3], 0, s[90:91]
	s_mov_b32 m0, s58
	s_add_u32 s6, s30, 0x40080
	global_load_lds_dwordx4 v[2:3], off
	v_lshl_add_u64 v[2:3], v[4:5], 0, s[90:91]
	s_mov_b32 m0, s59
	s_addc_u32 s7, s31, 0
	global_load_lds_dwordx4 v[2:3], off
	s_add_i32 m0, s45, 0x1c000
	v_lshl_add_u64 v[2:3], s[6:7], 0, v[134:135]
	global_load_lds_dwordx4 v[2:3], off
	v_lshl_add_u64 v[2:3], s[6:7], 0, v[130:131]
	s_add_i32 m0, s45, 0x1e000
	v_lshlrev_b32_e32 v18, 3, v17
	global_load_lds_dwordx4 v[2:3], off
	v_lshlrev_b32_e32 v2, 14, v13
	v_and_b32_e32 v2, 0xffff8000, v2
	v_lshl_add_u32 v2, v12, 11, v2
	v_and_b32_e32 v3, 1, v13
	v_lshl_or_b32 v2, v3, 6, v2
	v_lshl_add_u32 v140, v14, 1, v2
	v_lshlrev_b32_e32 v2, 14, v0
	v_and_b32_e32 v2, 0xffff8000, v2
	s_waitcnt vmcnt(6)
	v_lshl_add_u32 v2, v10, 11, v2
	v_and_b32_e32 v0, 1, v0
	s_cmpk_lt_u32 s16, 0x100
	v_lshl_or_b32 v0, v0, 6, v2
	v_readlane_b32 s4, v255, 33
	s_cselect_b64 s[16:17], -1, 0
	v_lshl_or_b32 v138, s57, 5, v18
	s_mov_b32 s68, 0
	v_cmp_eq_u32_e64 s[6:7], 0, v17
	v_mov_b32_e32 v141, v1
	v_lshl_add_u32 v142, v11, 1, v0
	v_mov_b32_e32 v143, v1
	v_add_u32_e32 v153, 0, v19
	v_readlane_b32 s69, v255, 14
	s_mov_b32 s70, s4
	s_andn2_b64 vcc, exec, s[8:9]
	s_cbranch_vccnz .Lpd_kv
	s_barrier
.Lpd_kv:
	s_barrier
	v_readlane_b32 s5, v255, 34
	s_branch .LBB0_338

.LBB0_529:
	v_bfe_u32 v18, v17, 4, 2
	v_and_b32_e32 v242, 15, v17
	v_lshlrev_b32_e32 v19, 4, v18
	v_lshlrev_b32_e32 v17, 2, v17
	s_lshl_b32 s11, s11, 5
	s_lshl_b32 s59, s22, 6
	v_lshl_or_b32 v19, v242, 6, v19
	s_lshl_b32 s22, s22, 13
	v_and_b32_e32 v17, 32, v17
	s_and_b32 s11, s11, 0x60
	s_add_i32 m0, s55, 0x18000
	v_lshl_add_u64 v[8:9], v[8:9], 0, s[90:91]
	v_bitop3_b32 v20, v19, s22, v17 bitop3:0xde
	s_lshl_b32 s22, s11, 7
	global_load_lds_dwordx4 v[8:9], off
	v_lshl_add_u64 v[6:7], v[6:7], 0, s[90:91]
	s_add_i32 m0, s55, 0x1a000
	s_add_i32 s68, s55, 0x8000
	s_add_i32 s69, s55, 0xa000
	v_bitop3_b32 v244, v19, s22, v17 bitop3:0xde
	global_load_lds_dwordx4 v[6:7], off
	v_lshl_add_u64 v[2:3], v[2:3], 0, s[90:91]
	s_mov_b32 m0, s68
	s_add_u32 s22, s36, 0x40080
	global_load_lds_dwordx4 v[2:3], off
	v_lshl_add_u64 v[2:3], v[4:5], 0, s[90:91]
	s_mov_b32 m0, s69
	s_addc_u32 s23, s37, 0
	global_load_lds_dwordx4 v[2:3], off
	s_add_i32 m0, s55, 0x1c000
	v_lshl_add_u64 v[2:3], s[22:23], 0, v[204:205]
	global_load_lds_dwordx4 v[2:3], off
	v_lshl_add_u64 v[2:3], s[22:23], 0, v[192:193]
	s_add_i32 m0, s55, 0x1e000
	s_cmpk_lt_u32 s10, 0x100
	global_load_lds_dwordx4 v[2:3], off
	s_cselect_b64 s[22:23], -1, 0
	s_cmp_lg_u64 s[8:9], 0
	s_movk_i32 s5, 0xe00
	v_cmp_eq_u32_e32 vcc, 0, v18
	s_cselect_b64 s[8:9], -1, 0
	v_lshrrev_b32_e32 v3, 1, v14
	v_mul_lo_u32 v2, v13, s5
	s_mov_b32 s4, 0xe000
	s_and_b64 s[24:25], vcc, s[8:9]
	v_mad_u64_u32 v[2:3], s[8:9], v3, s4, v[2:3]
	v_or_b32_e32 v2, v2, v15
	v_add_lshl_u32 v208, v2, v16, 1
	v_lshrrev_b32_e32 v2, 1, v0
	v_mul_lo_u32 v0, v10, s5
	s_waitcnt vmcnt(6)
	v_mad_u64_u32 v[2:3], s[8:9], v2, s4, v[0:1]
	v_or_b32_e32 v0, v2, v11
	v_readlane_b32 s4, v255, 43
	v_or_b32_e32 v243, s59, v242
	s_mov_b32 s70, 0
	v_lshl_or_b32 v245, v18, 3, s11
	v_mov_b32_e32 v209, v1
	v_add_lshl_u32 v210, v0, v12, 1
	v_mov_b32_e32 v211, v1
	v_add_u32_e32 v246, 0, v20
	v_readlane_b32 s72, v255, 15
	s_mov_b32 s38, s4
	s_andn2_b64 vcc, exec, s[20:21]
	s_cbranch_vccnz .Lpd_g2a
	s_barrier
.Lpd_g2a:
	s_barrier
	v_readlane_b32 s5, v255, 44
	s_branch .LBB0_532

.LBB0_573:
	v_bfe_u32 v18, v17, 4, 2
	s_lshl_b32 s10, s10, 5
	v_and_b32_e32 v241, 15, v17
	v_lshlrev_b32_e32 v19, 4, v18
	v_lshlrev_b32_e32 v17, 2, v17
	s_and_b32 s12, s10, 0x60
	s_add_i32 m0, s41, 0x18000
	v_lshl_add_u64 v[8:9], v[8:9], 0, s[90:91]
	v_lshl_or_b32 v19, v241, 6, v19
	s_lshl_b32 s11, s9, 13
	v_and_b32_e32 v17, 32, v17
	s_lshl_b32 s10, s12, 7
	global_load_lds_dwordx4 v[8:9], off
	v_lshl_add_u64 v[6:7], v[6:7], 0, s[90:91]
	s_add_i32 m0, s41, 0x1a000
	s_add_i32 s57, s41, 0x8000
	s_add_i32 s58, s41, 0xa000
	v_bitop3_b32 v243, v19, s10, v17 bitop3:0xde
	global_load_lds_dwordx4 v[6:7], off
	v_lshl_add_u64 v[2:3], v[2:3], 0, s[90:91]
	s_mov_b32 m0, s57
	s_add_u32 s10, s34, 0x40080
	v_bitop3_b32 v20, v19, s11, v17 bitop3:0xde
	global_load_lds_dwordx4 v[2:3], off
	v_lshl_add_u64 v[2:3], v[4:5], 0, s[90:91]
	s_mov_b32 m0, s58
	s_addc_u32 s11, s35, 0
	global_load_lds_dwordx4 v[2:3], off
	s_add_i32 m0, s41, 0x1c000
	v_lshl_add_u64 v[2:3], s[10:11], 0, v[204:205]
	global_load_lds_dwordx4 v[2:3], off
	v_lshl_add_u64 v[2:3], s[10:11], 0, v[192:193]
	s_add_i32 m0, s41, 0x1e000
	s_movk_i32 s5, 0xe00
	global_load_lds_dwordx4 v[2:3], off
	v_lshrrev_b32_e32 v3, 1, v14
	v_mul_lo_u32 v2, v13, s5
	s_mov_b32 s4, 0xe000
	v_mad_u64_u32 v[2:3], s[10:11], v3, s4, v[2:3]
	v_lshl_or_b32 v242, s9, 6, v241
	s_lshl_b32 s9, s9, 8
	v_or_b32_e32 v2, v2, v15
	s_add_i32 s59, s9, 0
	v_add_lshl_u32 v208, v2, v16, 1
	v_lshrrev_b32_e32 v2, 1, v0
	v_mul_lo_u32 v0, v10, s5
	s_waitcnt vmcnt(6)
	s_add_i32 s59, s59, 0x20400
	v_mad_u64_u32 v[2:3], s[10:11], v2, s4, v[0:1]
	s_cmpk_lt_u32 s8, 0x100
	v_or_b32_e32 v0, v2, v11
	v_readlane_b32 s4, v255, 43
	s_cselect_b64 s[22:23], -1, 0
	s_mov_b32 s68, 0
	v_cmp_eq_u32_e64 s[8:9], 0, v18
	v_lshl_or_b32 v244, v18, 3, s12
	v_mov_b32_e32 v209, v1
	v_add_lshl_u32 v210, v0, v12, 1
	v_mov_b32_e32 v211, v1
	v_add_u32_e32 v245, 0, v20
	v_readlane_b32 s70, v255, 15
	s_mov_b32 s71, s4
	s_andn2_b64 vcc, exec, s[20:21]
	s_cbranch_vccnz .Lpd_g2b
	s_barrier

.LBB0_665:
	s_add_u32 s14, s10, 0x6200000
	s_addc_u32 s15, s11, 0
	s_lshl_b64 s[8:9], s[8:9], 2
	s_add_u32 s4, s10, s8
	s_addc_u32 s5, s11, s9
	s_add_u32 s16, s4, 0xf110000
	s_addc_u32 s17, s5, 0
	v_bfe_u32 v17, v15, 4, 2
	s_add_u32 s18, s10, 0xef00000
	v_and_b32_e32 v16, 15, v15
	v_lshlrev_b32_e32 v19, 4, v17
	v_lshlrev_b32_e32 v15, 2, v15
	s_addc_u32 s19, s11, 0
	s_and_b32 s59, s22, 3
	v_lshl_or_b32 v139, s21, 6, v16
	v_lshl_or_b32 v16, v16, 6, v19
	s_lshl_b32 s4, s21, 13
	v_and_b32_e32 v15, 32, v15
	s_add_i32 m0, s55, 0x18000
	v_lshl_add_u64 v[8:9], v[8:9], 0, s[90:91]
	v_bitop3_b32 v19, v16, s4, v15 bitop3:0xde
	s_lshl_b32 s4, s59, 12
	global_load_lds_dwordx4 v[8:9], off
	v_lshl_add_u64 v[6:7], v[6:7], 0, s[90:91]
	s_add_i32 m0, s55, 0x1a000
	s_add_i32 s68, s55, 0x8000
	s_add_i32 s69, s55, 0xa000
	global_load_lds_dwordx4 v[6:7], off
	v_lshl_add_u64 v[2:3], v[2:3], 0, s[90:91]
	s_mov_b32 m0, s68
	s_add_u32 s8, s34, 0x40080
	global_load_lds_dwordx4 v[2:3], off
	v_lshl_add_u64 v[2:3], v[4:5], 0, s[90:91]
	s_mov_b32 m0, s69
	s_addc_u32 s9, s35, 0
	global_load_lds_dwordx4 v[2:3], off
	s_add_i32 m0, s55, 0x1c000
	v_lshl_add_u64 v[2:3], s[8:9], 0, v[134:135]
	global_load_lds_dwordx4 v[2:3], off
	v_lshl_add_u64 v[2:3], s[8:9], 0, v[130:131]
	s_add_i32 m0, s55, 0x1e000
	v_lshlrev_b32_e32 v18, 3, v17
	global_load_lds_dwordx4 v[2:3], off
	v_lshlrev_b32_e32 v2, 14, v13
	v_and_b32_e32 v2, 0xffff8000, v2
	v_lshl_add_u32 v2, v12, 11, v2
	v_and_b32_e32 v3, 1, v13
	v_lshl_or_b32 v2, v3, 6, v2
	v_lshl_add_u32 v140, v14, 1, v2
	v_lshlrev_b32_e32 v2, 14, v0
	v_and_b32_e32 v2, 0xffff8000, v2
	s_waitcnt vmcnt(6)
	v_lshl_add_u32 v2, v10, 11, v2
	v_and_b32_e32 v0, 1, v0
	v_bitop3_b32 v148, v16, s4, v15 bitop3:0xde
	s_cmpk_lt_u32 s20, 0x100
	v_lshl_or_b32 v0, v0, 6, v2
	v_readlane_b32 s4, v255, 43
	s_cselect_b64 s[20:21], -1, 0
	v_lshl_or_b32 v138, s59, 5, v18
	s_mov_b32 s70, 0
	v_cmp_eq_u32_e64 s[8:9], 0, v17
	v_mov_b32_e32 v141, v1
	v_lshl_add_u32 v142, v11, 1, v0
	v_mov_b32_e32 v143, v1
	v_add_u32_e32 v149, 0, v19
	v_readlane_b32 s71, v255, 15
	s_mov_b32 s72, s4
	s_andn2_b64 vcc, exec, s[12:13]
	s_cbranch_vccnz .Lpd_g3
	s_barrier

.LBB0_763:
	s_add_u32 s14, s8, 0x4200000
	s_addc_u32 s15, s9, 0
	s_lshl_b64 s[16:17], s[10:11], 2
	s_add_u32 s4, s8, s16
	s_addc_u32 s5, s9, s17
	v_bfe_u32 v17, v16, 4, 2
	s_add_u32 s16, s4, 0xf110000
	v_and_b32_e32 v18, 15, v16
	v_lshlrev_b32_e32 v19, 4, v17
	v_lshlrev_b32_e32 v16, 2, v16
	s_addc_u32 s17, s5, 0
	v_lshl_or_b32 v230, s20, 6, v18
	v_lshl_or_b32 v18, v18, 6, v19
	s_lshl_b32 s4, s20, 13
	v_and_b32_e32 v16, 32, v16
	v_bitop3_b32 v19, v18, s4, v16 bitop3:0xde
	s_lshl_b32 s4, s19, 5
	s_and_b32 s4, s4, 0x60
	s_add_i32 m0, s56, 0x18000
	v_lshl_add_u64 v[8:9], v[8:9], 0, s[90:91]
	s_lshl_b32 s5, s4, 7
	global_load_lds_dwordx4 v[8:9], off
	v_lshl_add_u64 v[6:7], v[6:7], 0, s[90:91]
	s_add_i32 m0, s56, 0x1a000
	s_add_i32 s68, s56, 0x8000
	s_add_i32 s69, s56, 0xa000
	global_load_lds_dwordx4 v[6:7], off
	v_lshl_add_u64 v[2:3], v[2:3], 0, s[90:91]
	s_mov_b32 m0, s68
	s_add_u32 s20, s34, 0x40080
	global_load_lds_dwordx4 v[2:3], off
	v_lshl_add_u64 v[2:3], v[4:5], 0, s[90:91]
	s_mov_b32 m0, s69
	s_addc_u32 s21, s35, 0
	global_load_lds_dwordx4 v[2:3], off
	s_add_i32 m0, s56, 0x1c000
	v_lshl_add_u64 v[2:3], s[20:21], 0, v[0:1]
	global_load_lds_dwordx4 v[2:3], off
	v_lshl_add_u64 v[2:3], s[20:21], 0, v[190:191]
	s_add_i32 m0, s56, 0x1e000
	s_cmpk_lt_u32 s18, 0x100
	global_load_lds_dwordx4 v[2:3], off
	v_lshlrev_b32_e32 v2, 14, v14
	v_and_b32_e32 v2, 0xffff8000, v2
	v_lshl_add_u32 v2, v13, 11, v2
	v_and_b32_e32 v3, 1, v14
	v_lshl_or_b32 v2, v3, 6, v2
	v_lshl_add_u32 v204, v15, 1, v2
	v_lshlrev_b32_e32 v2, 14, v10
	v_and_b32_e32 v2, 0xffff8000, v2
	s_waitcnt vmcnt(6)
	s_cselect_b64 s[18:19], -1, 0
	s_cmp_lg_u64 s[8:9], 0
	v_lshl_add_u32 v2, v11, 11, v2
	v_and_b32_e32 v3, 1, v10
	v_bitop3_b32 v231, v18, s5, v16 bitop3:0xde
	v_cmp_eq_u32_e32 vcc, 0, v17
	s_cselect_b64 s[8:9], -1, 0
	v_lshl_or_b32 v241, v17, 3, s4
	v_lshl_or_b32 v2, v3, 6, v2
	v_readlane_b32 s4, v255, 43
	s_mov_b32 s70, 0
	s_and_b64 s[20:21], vcc, s[8:9]
	v_mov_b32_e32 v205, v1
	v_lshl_add_u32 v206, v12, 1, v2
	v_mov_b32_e32 v207, v1
	v_add_u32_e32 v242, 0, v19
	v_readlane_b32 s71, v255, 15
	s_mov_b32 s72, s4
	s_andn2_b64 vcc, exec, s[12:13]
	s_cbranch_vccnz .Lpd_g4
	s_barrier

.LBB0_851:
	s_add_u32 s18, s12, 0x6200000
	s_addc_u32 s19, s13, 0
	s_lshl_b64 s[10:11], s[10:11], 2
	v_lshrrev_b32_e32 v16, 1, v150
	s_add_u32 s4, s12, s10
	v_and_b32_e32 v16, 24, v16
	s_addc_u32 s5, s13, s11
	v_and_b32_e32 v15, 15, v150
	v_lshlrev_b32_e32 v17, 1, v16
	s_add_u32 s10, s4, 0xf110000
	v_lshl_or_b32 v151, s9, 6, v15
	v_lshl_or_b32 v15, v15, 6, v17
	v_lshlrev_b32_e32 v17, 2, v150
	s_addc_u32 s11, s5, 0
	s_lshl_b32 s4, s9, 13
	v_and_b32_e32 v17, 32, v17
	v_bitop3_b32 v18, v15, s4, v17 bitop3:0xde
	s_lshl_b32 s4, s8, 5
	s_and_b32 s4, s4, 0x60
	s_add_i32 m0, s56, 0x18000
	v_lshl_add_u64 v[8:9], v[8:9], 0, s[90:91]
	s_lshl_b32 s5, s4, 7
	global_load_lds_dwordx4 v[8:9], off
	v_lshl_add_u64 v[6:7], v[6:7], 0, s[90:91]
	s_add_i32 m0, s56, 0x1a000
	s_add_i32 s68, s56, 0x8000
	s_add_i32 s69, s56, 0xa000
	global_load_lds_dwordx4 v[6:7], off
	v_lshl_add_u64 v[2:3], v[2:3], 0, s[90:91]
	s_mov_b32 m0, s68
	s_add_u32 s8, s34, 0x40080
	global_load_lds_dwordx4 v[2:3], off
	v_lshl_add_u64 v[2:3], v[4:5], 0, s[90:91]
	s_mov_b32 m0, s69
	s_addc_u32 s9, s35, 0
	global_load_lds_dwordx4 v[2:3], off
	s_add_i32 m0, s56, 0x1c000
	v_lshl_add_u64 v[2:3], s[8:9], 0, v[134:135]
	global_load_lds_dwordx4 v[2:3], off
	v_lshl_add_u64 v[2:3], s[8:9], 0, v[130:131]
	s_add_i32 m0, s56, 0x1e000
	v_and_b32_e32 v4, 1, v13
	global_load_lds_dwordx4 v[2:3], off
	v_lshlrev_b32_e32 v3, 14, v13
	v_and_b32_e32 v3, 0xffff8000, v3
	v_lshl_add_u32 v3, v12, 11, v3
	v_lshl_or_b32 v3, v4, 6, v3
	v_lshl_add_u32 v138, v14, 1, v3
	v_lshlrev_b32_e32 v3, 14, v0
	v_and_b32_e32 v3, 0xffff8000, v3
	s_waitcnt vmcnt(6)
	v_lshl_add_u32 v3, v10, 11, v3
	v_and_b32_e32 v0, 1, v0
	v_bitop3_b32 v152, v15, s5, v17 bitop3:0xde
	s_cmpk_lt_u32 s20, 0x100
	v_or_b32_e32 v2, s4, v16
	v_lshl_or_b32 v0, v0, 6, v3
	v_readlane_b32 s4, v255, 17
	s_cselect_b64 s[20:21], -1, 0
	v_mov_b32_e32 v139, v1
	v_lshl_add_u32 v140, v11, 1, v0
	v_mov_b32_e32 v141, v1
	s_mov_b32 s70, 0
	v_add_u32_e32 v153, 0, v18
	v_lshlrev_b32_e32 v0, 1, v2
	s_mov_b32 s72, s4
	v_readlane_b32 s71, v255, 16
	s_andn2_b64 vcc, exec, s[16:17]
	s_cbranch_vccnz .Lpd_g5
	s_barrier
.Lpd_g5:
	s_barrier
	v_readlane_b32 s5, v255, 18
	s_branch .LBB0_854

.LBB0_905:
	s_add_u32 s16, s10, 0x4200000
	s_addc_u32 s17, s11, 0
	s_lshl_b64 s[18:19], s[54:55], 16
	s_add_u32 s4, s10, s18
	s_addc_u32 s5, s11, s19
	v_bfe_u32 v17, v16, 4, 2
	s_add_u32 s18, s4, 0xf140000
	v_and_b32_e32 v18, 15, v16
	v_lshlrev_b32_e32 v19, 4, v17
	v_lshlrev_b32_e32 v16, 2, v16
	s_addc_u32 s19, s5, 0
	v_lshl_or_b32 v230, s20, 6, v18
	v_lshl_or_b32 v18, v18, 6, v19
	s_lshl_b32 s4, s20, 13
	v_and_b32_e32 v16, 32, v16
	v_bitop3_b32 v19, v18, s4, v16 bitop3:0xde
	s_lshl_b32 s4, s9, 5
	s_and_b32 s4, s4, 0x60
	s_add_i32 m0, s58, 0x18000
	v_lshl_add_u64 v[8:9], v[8:9], 0, s[90:91]
	s_lshl_b32 s5, s4, 7
	global_load_lds_dwordx4 v[8:9], off
	v_lshl_add_u64 v[6:7], v[6:7], 0, s[90:91]
	s_add_i32 m0, s58, 0x1a000
	s_add_i32 s54, s58, 0x8000
	s_add_i32 s55, s58, 0xa000
	global_load_lds_dwordx4 v[6:7], off
	v_lshl_add_u64 v[2:3], v[2:3], 0, s[90:91]
	s_mov_b32 m0, s54
	s_add_u32 s20, s36, 0x100080
	global_load_lds_dwordx4 v[2:3], off
	v_lshl_add_u64 v[2:3], v[4:5], 0, s[90:91]
	s_mov_b32 m0, s55
	s_addc_u32 s21, s37, 0
	global_load_lds_dwordx4 v[2:3], off
	s_add_i32 m0, s58, 0x1c000
	v_lshl_add_u64 v[2:3], s[20:21], 0, v[0:1]
	global_load_lds_dwordx4 v[2:3], off
	v_lshl_add_u64 v[2:3], s[20:21], 0, v[190:191]
	s_add_i32 m0, s58, 0x1e000
	s_cmpk_lt_u32 s8, 0x100
	global_load_lds_dwordx4 v[2:3], off
	v_lshlrev_b32_e32 v2, 16, v14
	v_and_b32_e32 v2, 0xfffe0000, v2
	v_lshl_add_u32 v2, v13, 13, v2
	v_and_b32_e32 v3, 1, v14
	v_lshl_or_b32 v2, v3, 6, v2
	v_lshl_add_u32 v204, v15, 1, v2
	v_lshlrev_b32_e32 v2, 16, v10
	v_and_b32_e32 v2, 0xfffe0000, v2
	s_waitcnt vmcnt(6)
	s_cselect_b64 s[20:21], -1, 0
	s_cmp_lg_u64 s[10:11], 0
	v_lshl_add_u32 v2, v11, 13, v2
	v_and_b32_e32 v3, 1, v10
	v_bitop3_b32 v231, v18, s5, v16 bitop3:0xde
	v_cmp_eq_u32_e32 vcc, 0, v17
	s_cselect_b64 s[8:9], -1, 0
	v_lshl_or_b32 v241, v17, 3, s4
	v_lshl_or_b32 v2, v3, 6, v2
	v_readlane_b32 s4, v255, 43
	s_mov_b32 s69, 0
	s_and_b64 s[22:23], vcc, s[8:9]
	v_mov_b32_e32 v205, v1
	v_lshl_add_u32 v206, v12, 1, v2
	v_mov_b32_e32 v207, v1
	v_add_u32_e32 v242, 0, v19
	v_readlane_b32 s70, v255, 15
	s_mov_b32 s71, s4
	s_andn2_b64 vcc, exec, s[14:15]
	s_cbranch_vccnz .Lpd_g6a
	s_barrier

.LBB0_943:
	v_bfe_u32 v18, v16, 4, 2
	s_add_u32 s10, s10, 0x4200000
	v_and_b32_e32 v17, 15, v16
	v_lshlrev_b32_e32 v19, 4, v18
	v_lshlrev_b32_e32 v16, 2, v16
	s_addc_u32 s11, s11, 0
	v_lshl_or_b32 v228, s14, 6, v17
	v_lshl_or_b32 v17, v17, 6, v19
	s_lshl_b32 s4, s14, 13
	v_and_b32_e32 v16, 32, v16
	v_bitop3_b32 v19, v17, s4, v16 bitop3:0xde
	s_lshl_b32 s4, s7, 5
	s_and_b32 s4, s4, 0x60
	s_add_i32 m0, s37, 0x18000
	v_lshl_add_u64 v[8:9], v[8:9], 0, s[90:91]
	s_lshl_b32 s5, s4, 7
	global_load_lds_dwordx4 v[8:9], off
	v_lshl_add_u64 v[6:7], v[6:7], 0, s[90:91]
	s_add_i32 m0, s37, 0x1a000
	s_add_i32 s41, s37, 0x8000
	s_add_i32 s42, s37, 0xa000
	global_load_lds_dwordx4 v[6:7], off
	v_lshl_add_u64 v[2:3], v[2:3], 0, s[90:91]
	s_mov_b32 m0, s41
	s_add_u32 s14, s26, 0x100080
	global_load_lds_dwordx4 v[2:3], off
	v_lshl_add_u64 v[2:3], v[4:5], 0, s[90:91]
	s_mov_b32 m0, s42
	s_addc_u32 s15, s27, 0
	global_load_lds_dwordx4 v[2:3], off
	s_add_i32 m0, s37, 0x1c000
	v_lshl_add_u64 v[2:3], s[14:15], 0, v[0:1]
	global_load_lds_dwordx4 v[2:3], off
	v_lshl_add_u64 v[2:3], s[14:15], 0, v[202:203]
	s_add_i32 m0, s37, 0x1e000
	v_bitop3_b32 v229, v17, s5, v16 bitop3:0xde
	global_load_lds_dwordx4 v[2:3], off
	v_lshlrev_b32_e32 v2, 16, v14
	v_and_b32_e32 v2, 0xfffe0000, v2
	v_lshl_add_u32 v2, v13, 13, v2
	v_and_b32_e32 v3, 1, v14
	v_lshl_or_b32 v2, v3, 6, v2
	v_lshl_add_u32 v208, v15, 1, v2
	v_lshlrev_b32_e32 v2, 16, v10
	v_and_b32_e32 v2, 0xfffe0000, v2
	s_waitcnt vmcnt(6)
	v_lshl_add_u32 v2, v11, 13, v2
	v_and_b32_e32 v3, 1, v10
	s_cmpk_lt_u32 s6, 0x100
	v_lshl_or_b32 v230, v18, 3, s4
	v_lshl_or_b32 v2, v3, 6, v2
	v_readlane_b32 s4, v255, 43
	s_cselect_b64 s[14:15], -1, 0
	v_mov_b32_e32 v209, v1
	v_lshl_add_u32 v210, v12, 1, v2
	v_mov_b32_e32 v211, v1
	s_mov_b32 s43, 0
	v_add_u32_e32 v231, 0, v19
	v_readlane_b32 s54, v255, 15
	s_mov_b32 s55, s4
	s_andn2_b64 vcc, exec, s[12:13]
	s_cbranch_vccnz .Lpd_g6b
	s_barrier
